# P0 w_in weight conversion fast path (4 steps per workgroup, loads issued ahead, double-buffered LDS tile); on top of v101
# speedup vs baseline: 1.0085x; 1.0085x over previous
; __device__ __forceinline__ int perm_n0(int type, int p0, int& use1) {
;     ...
;   if (type == PM_IN) {
;     if (p0 < 768) return p0;
;     if (p0 < 1024) { const int q = p0 - 768; return (q == 0) ? 768 : (q == 128 ? 800 : -1); }
;     if (p0 < 3072) { const int tt = p0 - 1024, tile = tt >> 8, q = tt & 255, half = q >> 7, sub = (q >> 6) & 1, i = q & 63; return 832 + tile * 256 + sub * 128 + half * 64 + i; }
;     return 2880 + (p0 - 3072);
;   } else if (type == PM_UQ) {
;     if (p0 < 1024) return (p0 >> 7) * 192 + (p0 & 127);
;     const int tt = p0 - 1024, tile = tt >> 8, q = tt & 255, half = q >> 7, hh = (q >> 5) & 3; return (4 * tile + hh) * 192 + 128 + 32 * half;
;   } else if (type == PM_GU) {
;     const int tile = p0 >> 8, q = p0 & 255; if (q < 128) return tile * 128 + q; use1 = 1; return tile * 128 + q - 128;
;   }
;   return p0;
; }
; __device__ __forceinline__ void transpose_w(const float* __restrict__ src0, const float* __restrict__ src1, int K, int N, bf16_t* __restrict__ dst, int P, int type, float* tl, int first, int stride) {
;   const int tid = threadIdx.x, nkt = K / 128, ntiles = nkt * (P / 64), c32 = tid & 31, kq = tid >> 5;
;   for (int t = first; t < ntiles; t += stride) {
;     const int pi = t / nkt, ki = t - pi * nkt, p0 = pi * 64, k0 = ki * 128;
;     int u0, u1; const int n0a = perm_n0(type, p0, u0), n0b = perm_n0(type, p0 + 32, u1);
;     const float* sa = (u0 ? src1 : src0) + (size_t)k0 * N + (n0a < 0 ? 0 : n0a) + c32; const float* sb = (u1 ? src1 : src0) + (size_t)k0 * N + (n0b < 0 ? 0 : n0b) + c32;
;     float va[8], vb[8];
; #pragma unroll
;     for (int i = 0; i < 8; ++i) { va[i] = sa[(size_t)(kq + 16 * i) * N]; vb[i] = sb[(size_t)(kq + 16 * i) * N]; }
;     __syncthreads();
; #pragma unroll
;     for (int i = 0; i < 8; ++i) { tl[(kq + 16 * i) * 33 + c32] = n0a < 0 ? 0.f : va[i]; tl[128 * 33 + (kq + 16 * i) * 33 + c32] = n0b < 0 ? 0.f : vb[i]; }
;     __syncthreads();
;     const int row = tid >> 4, kc = (tid & 15) * 8;
; #pragma unroll
;     for (int h = 0; h < 2; ++h) { const float* q = tl + h * 128 * 33 + kc * 33 + row;
;       u32x4 w; w.x = cvt_pk_bf16(q[0], q[33]); w.y = cvt_pk_bf16(q[66], q[99]); w.z = cvt_pk_bf16(q[132], q[165]); w.w = cvt_pk_bf16(q[198], q[231]);
;       *(u32x4*)(dst + (size_t)(p0 + h * 32 + row) * K + k0 + kc) = w; }
.LBB0_17:
	s_add_u32 s10, s74, 0x7080000
	s_addc_u32 s11, s75, 0
	s_add_u32 s8, s74, 0x6c80000
	s_addc_u32 s9, s75, 0
	s_add_u32 s80, s74, 0x6e80000
	s_addc_u32 s81, s75, 0
	s_cmp_lt_i32 s76, 1
	s_cselect_b64 s[0:1], -1, 0
	s_cmp_gt_i32 s77, 0
	s_cselect_b64 s[2:3], -1, 0
	s_and_b64 s[0:1], s[0:1], s[2:3]
	s_andn2_b64 vcc, exec, s[0:1]
	v_and_b32_e32 v152, 31, v187
	v_lshrrev_b32_e32 v153, 4, v187
	v_lshlrev_b32_e32 v192, 3, v187
	s_cbranch_vccnz .LBB0_103
	v_and_b32_e32 v32, 0x78, v192
	v_lshrrev_b32_e32 v33, 5, v187
	v_mul_u32_u24_e32 v2, 0x84, v32
	v_lshlrev_b32_e32 v3, 2, v153
	v_add3_u32 v22, 0, v2, v3
	v_mul_u32_u24_e32 v2, 33, v33
	v_lshlrev_b32_e32 v0, 2, v152
	v_lshlrev_b32_e32 v2, 2, v2
	v_add3_u32 v24, 0, v2, v0
	s_cmpk_gt_i32 s14, 0x3ff
	v_mov_b32_e32 v1, 0
	v_add3_u32 v23, 0, v0, v2
	v_add_u32_e32 v25, 0x840, v24
	v_add_u32_e32 v26, 0x1080, v24
	v_add_u32_e32 v27, 0x18c0, v24
	v_add_u32_e32 v28, 0x2100, v24
	v_add_u32_e32 v29, 0x2940, v24
	v_add_u32_e32 v30, 0x3180, v24
	v_add_u32_e32 v31, 0x39c0, v24
	s_cbranch_scc1 .LBB0_36
	s_cmpk_eq_i32 s78, 0x100
	s_cbranch_scc0 .Lwin_orig
	v_lshrrev_b32_e32 v46, 5, v187
	v_and_b32_e32 v47, 31, v187
	s_movk_i32 s0, 0xf40
	v_add_u32_e32 v34, 0, v46
	v_mad_u32_u24 v34, v34, s0, v47
	v_lshlrev_b32_e32 v34, 2, v34
	v_add_u32_e32 v35, 16, v46
	v_mad_u32_u24 v35, v35, s0, v47
	v_lshlrev_b32_e32 v35, 2, v35
	v_add_u32_e32 v36, 32, v46
	v_mad_u32_u24 v36, v36, s0, v47
	v_lshlrev_b32_e32 v36, 2, v36
	v_add_u32_e32 v37, 48, v46
	v_mad_u32_u24 v37, v37, s0, v47
	v_lshlrev_b32_e32 v37, 2, v37
	v_add_u32_e32 v38, 64, v46
	v_mad_u32_u24 v38, v38, s0, v47
	v_lshlrev_b32_e32 v38, 2, v38
	v_add_u32_e32 v39, 80, v46
	v_mad_u32_u24 v39, v39, s0, v47
	v_lshlrev_b32_e32 v39, 2, v39
	v_add_u32_e32 v40, 96, v46
	v_mad_u32_u24 v40, v40, s0, v47
	v_lshlrev_b32_e32 v40, 2, v40
	v_add_u32_e32 v41, 112, v46
	v_mad_u32_u24 v41, v41, s0, v47
	v_lshlrev_b32_e32 v41, 2, v41
	v_mad_u32_u24 v42, v46, 33, v47
	v_lshlrev_b32_e32 v42, 2, v42
	v_lshrrev_b32_e32 v47, 3, v187
	v_and_b32_e32 v47, 12, v47
	v_and_b32_e32 v46, 3, v187
	v_or_b32_e32 v47, v47, v46
	v_lshlrev_b32_e32 v47, 3, v47
	v_lshrrev_b32_e32 v46, 4, v187
	v_and_b32_e32 v46, 24, v46
	v_bfe_u32 v43, v187, 2, 3
	v_or_b32_e32 v46, v46, v43
	v_mad_u32_u24 v43, v47, 33, v46
	v_lshlrev_b32_e32 v43, 2, v43
	v_add_u32_e32 v44, 0x4200, v43
	v_lshl_add_u32 v45, v46, 11, v47
	v_lshlrev_b32_e32 v45, 1, v45
	s_lshr_b32 s0, s14, 4
	s_and_b32 s1, s14, 15
	s_mul_i32 s2, s1, 0x1e8000
	s_waitcnt lgkmcnt(0)
	s_add_u32 s86, s44, s2
	s_addc_u32 s87, s45, 0
	s_lshl_b32 s2, s0, 18
	s_lshl_b32 s3, s1, 8
	s_add_u32 s2, s2, s3
	s_add_u32 s84, s74, s2
	s_addc_u32 s85, s75, 0
	s_lshl_b32 s2, s0, 6
	s_cmp_lt_u32 s0, 12
	s_cselect_b64 s[4:5], 0, -1
	s_movk_i32 s3, 0x300
	s_cmp_eq_u32 s0, 14
	s_cselect_b32 s3, 0x320, s3
	s_cmp_lt_u32 s0, 12
	s_cselect_b32 s2, s2, s3
	s_and_b32 s3, s0, 1
	s_cmp_lg_u32 s3, 0
	s_cselect_b64 s[6:7], -1, 0
	s_and_b64 s[6:7], s[6:7], s[4:5]
	s_lshr_b32 s3, s0, 2
	s_lshl_b32 s3, s3, 8
	s_and_b32 s15, s0, 1
	s_lshl_b32 s15, s15, 7
	s_add_u32 s3, s3, s15
	s_and_b32 s15, s0, 2
	s_lshl_b32 s15, s15, 5
	s_add_u32 s3, s3, s15
	s_add_u32 s3, s3, 0x340
	s_lshl_b32 s33, s0, 6
	s_add_u32 s33, s33, 0xb40
	s_lshl_b32 s88, s2, 2
	s_add_u32 s82, s86, s88
	s_addc_u32 s83, s87, 0
	global_load_dword v64, v34, s[82:83]
	global_load_dword v72, v34, s[82:83] offset:128
	global_load_dword v65, v35, s[82:83]
	global_load_dword v73, v35, s[82:83] offset:128
	global_load_dword v66, v36, s[82:83]
	global_load_dword v74, v36, s[82:83] offset:128
	global_load_dword v67, v37, s[82:83]
	global_load_dword v75, v37, s[82:83] offset:128
	global_load_dword v68, v38, s[82:83]
	global_load_dword v76, v38, s[82:83] offset:128
	global_load_dword v69, v39, s[82:83]
	global_load_dword v77, v39, s[82:83] offset:128
	global_load_dword v70, v40, s[82:83]
	global_load_dword v78, v40, s[82:83] offset:128
	global_load_dword v71, v41, s[82:83]
	global_load_dword v79, v41, s[82:83] offset:128
	s_lshl_b32 s88, s3, 2
	s_add_u32 s82, s86, s88
	s_addc_u32 s83, s87, 0
	global_load_dword v80, v34, s[82:83]
	global_load_dword v88, v34, s[82:83] offset:128
	global_load_dword v81, v35, s[82:83]
	global_load_dword v89, v35, s[82:83] offset:128
	global_load_dword v82, v36, s[82:83]
	global_load_dword v90, v36, s[82:83] offset:128
	global_load_dword v83, v37, s[82:83]
	global_load_dword v91, v37, s[82:83] offset:128
	global_load_dword v84, v38, s[82:83]
	global_load_dword v92, v38, s[82:83] offset:128
	global_load_dword v85, v39, s[82:83]
	global_load_dword v93, v39, s[82:83] offset:128
	global_load_dword v86, v40, s[82:83]
	global_load_dword v94, v40, s[82:83] offset:128
	global_load_dword v87, v41, s[82:83]
	global_load_dword v95, v41, s[82:83] offset:128
	s_add_u32 s3, s3, 0x400
	s_lshl_b32 s88, s3, 2
	s_add_u32 s82, s86, s88
	s_addc_u32 s83, s87, 0
	global_load_dword v96, v34, s[82:83]
	global_load_dword v104, v34, s[82:83] offset:128
	global_load_dword v97, v35, s[82:83]
	global_load_dword v105, v35, s[82:83] offset:128
	global_load_dword v98, v36, s[82:83]
	global_load_dword v106, v36, s[82:83] offset:128
	global_load_dword v99, v37, s[82:83]
	global_load_dword v107, v37, s[82:83] offset:128
	global_load_dword v100, v38, s[82:83]
	global_load_dword v108, v38, s[82:83] offset:128
	global_load_dword v101, v39, s[82:83]
	global_load_dword v109, v39, s[82:83] offset:128
	global_load_dword v102, v40, s[82:83]
	global_load_dword v110, v40, s[82:83] offset:128
	global_load_dword v103, v41, s[82:83]
	global_load_dword v111, v41, s[82:83] offset:128
	s_waitcnt vmcnt(32)
; __device__ __forceinline__ unsigned cvt_pk_bf16(float lo, float hi) { unsigned r; asm volatile("v_cvt_pk_bf16_f32 %0, %1, %2" : "=v"(r) : "v"(lo), "v"(hi)); return r; }
; __device__ __forceinline__ void transpose_w(const float* __restrict__ src0, const float* __restrict__ src1, int K, int N, bf16_t* __restrict__ dst, int P, int type, float* tl, int first, int stride) {
;     ...
;   for (int t = first; t < ntiles; t += stride) {
;     const int pi = t / nkt, ki = t - pi * nkt, p0 = pi * 64, k0 = ki * 128;
;     int u0, u1; const int n0a = perm_n0(type, p0, u0), n0b = perm_n0(type, p0 + 32, u1);
;     const float* sa = (u0 ? src1 : src0) + (size_t)k0 * N + (n0a < 0 ? 0 : n0a) + c32; const float* sb = (u1 ? src1 : src0) + (size_t)k0 * N + (n0b < 0 ? 0 : n0b) + c32;
;     float va[8], vb[8];
; #pragma unroll
;     for (int i = 0; i < 8; ++i) { va[i] = sa[(size_t)(kq + 16 * i) * N]; vb[i] = sb[(size_t)(kq + 16 * i) * N]; }
;     __syncthreads();
; #pragma unroll
;     for (int i = 0; i < 8; ++i) { tl[(kq + 16 * i) * 33 + c32] = n0a < 0 ? 0.f : va[i]; tl[128 * 33 + (kq + 16 * i) * 33 + c32] = n0b < 0 ? 0.f : vb[i]; }
;     __syncthreads();
;     const int row = tid >> 4, kc = (tid & 15) * 8;
; #pragma unroll
;     for (int h = 0; h < 2; ++h) { const float* q = tl + h * 128 * 33 + kc * 33 + row;
;       u32x4 w; w.x = cvt_pk_bf16(q[0], q[33]); w.y = cvt_pk_bf16(q[66], q[99]); w.z = cvt_pk_bf16(q[132], q[165]); w.w = cvt_pk_bf16(q[198], q[231]);
;       *(u32x4*)(dst + (size_t)(p0 + h * 32 + row) * K + k0 + kc) = w; }
	s_lshl_b32 s88, s33, 2
	s_add_u32 s82, s86, s88
	s_addc_u32 s83, s87, 0
	global_load_dword v112, v34, s[82:83]
	global_load_dword v120, v34, s[82:83] offset:128
	global_load_dword v113, v35, s[82:83]
	global_load_dword v121, v35, s[82:83] offset:128
	global_load_dword v114, v36, s[82:83]
	global_load_dword v122, v36, s[82:83] offset:128
	global_load_dword v115, v37, s[82:83]
	global_load_dword v123, v37, s[82:83] offset:128
	global_load_dword v116, v38, s[82:83]
	global_load_dword v124, v38, s[82:83] offset:128
	global_load_dword v117, v39, s[82:83]
	global_load_dword v125, v39, s[82:83] offset:128
	global_load_dword v118, v40, s[82:83]
	global_load_dword v126, v40, s[82:83] offset:128
	global_load_dword v119, v41, s[82:83]
	global_load_dword v127, v41, s[82:83] offset:128
	v_cndmask_b32_e64 v64, v64, 0, s[6:7]
	v_cndmask_b32_e64 v72, v72, 0, s[4:5]
	v_cndmask_b32_e64 v65, v65, 0, s[6:7]
	v_cndmask_b32_e64 v73, v73, 0, s[4:5]
	v_cndmask_b32_e64 v66, v66, 0, s[6:7]
	v_cndmask_b32_e64 v74, v74, 0, s[4:5]
	v_cndmask_b32_e64 v67, v67, 0, s[6:7]
	v_cndmask_b32_e64 v75, v75, 0, s[4:5]
	v_cndmask_b32_e64 v68, v68, 0, s[6:7]
	v_cndmask_b32_e64 v76, v76, 0, s[4:5]
	v_cndmask_b32_e64 v69, v69, 0, s[6:7]
	v_cndmask_b32_e64 v77, v77, 0, s[4:5]
	v_cndmask_b32_e64 v70, v70, 0, s[6:7]
	v_cndmask_b32_e64 v78, v78, 0, s[4:5]
	v_cndmask_b32_e64 v71, v71, 0, s[6:7]
	v_cndmask_b32_e64 v79, v79, 0, s[4:5]
	ds_write_b32 v42, v64 offset:0
	ds_write_b32 v42, v72 offset:16896
	ds_write_b32 v42, v65 offset:2112
	ds_write_b32 v42, v73 offset:19008
	ds_write_b32 v42, v66 offset:4224
	ds_write_b32 v42, v74 offset:21120
	ds_write_b32 v42, v67 offset:6336
	ds_write_b32 v42, v75 offset:23232
	ds_write_b32 v42, v68 offset:8448
	ds_write_b32 v42, v76 offset:25344
	ds_write_b32 v42, v69 offset:10560
	ds_write_b32 v42, v77 offset:27456
	ds_write_b32 v42, v70 offset:12672
	ds_write_b32 v42, v78 offset:29568
	ds_write_b32 v42, v71 offset:14784
	ds_write_b32 v42, v79 offset:31680
	s_waitcnt lgkmcnt(0)
	s_barrier
	ds_read_b32 v128, v43 offset:0
	ds_read_b32 v129, v43 offset:132
	ds_read_b32 v130, v43 offset:264
	ds_read_b32 v131, v43 offset:396
	ds_read_b32 v132, v43 offset:528
	ds_read_b32 v133, v43 offset:660
	ds_read_b32 v134, v43 offset:792
	ds_read_b32 v135, v43 offset:924
	ds_read_b32 v136, v44 offset:0
	ds_read_b32 v137, v44 offset:132
	ds_read_b32 v138, v44 offset:264
	ds_read_b32 v139, v44 offset:396
	ds_read_b32 v140, v44 offset:528
	ds_read_b32 v141, v44 offset:660
	ds_read_b32 v142, v44 offset:792
	ds_read_b32 v143, v44 offset:924
	s_waitcnt lgkmcnt(8)
	v_cvt_pk_bf16_f32 v48, v128, v129
	v_cvt_pk_bf16_f32 v49, v130, v131
	v_cvt_pk_bf16_f32 v50, v132, v133
	v_cvt_pk_bf16_f32 v51, v134, v135
	global_store_dwordx4 v45, v[48:51], s[84:85]
	s_waitcnt lgkmcnt(0)
	v_cvt_pk_bf16_f32 v52, v136, v137
	v_cvt_pk_bf16_f32 v53, v138, v139
	v_cvt_pk_bf16_f32 v54, v140, v141
	v_cvt_pk_bf16_f32 v55, v142, v143
	s_add_u32 s4, s84, 0x20000
	s_addc_u32 s5, s85, 0
	global_store_dwordx4 v45, v[52:55], s[4:5]
	s_add_u32 s84, s84, 0x400000
	s_addc_u32 s85, s85, 0
	s_waitcnt vmcnt(34)
	ds_write_b32 v42, v80 offset:33792
	ds_write_b32 v42, v88 offset:50688
	ds_write_b32 v42, v81 offset:35904
	ds_write_b32 v42, v89 offset:52800
	ds_write_b32 v42, v82 offset:38016
	ds_write_b32 v42, v90 offset:54912
	ds_write_b32 v42, v83 offset:40128
	ds_write_b32 v42, v91 offset:57024
	ds_write_b32 v42, v84 offset:42240
	ds_write_b32 v42, v92 offset:59136
	ds_write_b32 v42, v85 offset:44352
	ds_write_b32 v42, v93 offset:61248
	ds_write_b32 v42, v86 offset:46464
	ds_write_b32 v42, v94 offset:63360
	ds_write_b32 v42, v87 offset:48576
	ds_write_b32 v42, v95 offset:65472
	s_waitcnt lgkmcnt(0)
	s_barrier
; __device__ __forceinline__ unsigned cvt_pk_bf16(float lo, float hi) { unsigned r; asm volatile("v_cvt_pk_bf16_f32 %0, %1, %2" : "=v"(r) : "v"(lo), "v"(hi)); return r; }
; __device__ __forceinline__ void transpose_w(const float* __restrict__ src0, const float* __restrict__ src1, int K, int N, bf16_t* __restrict__ dst, int P, int type, float* tl, int first, int stride) {
;     ...
;   for (int t = first; t < ntiles; t += stride) {
;     const int pi = t / nkt, ki = t - pi * nkt, p0 = pi * 64, k0 = ki * 128;
;     int u0, u1; const int n0a = perm_n0(type, p0, u0), n0b = perm_n0(type, p0 + 32, u1);
;     const float* sa = (u0 ? src1 : src0) + (size_t)k0 * N + (n0a < 0 ? 0 : n0a) + c32; const float* sb = (u1 ? src1 : src0) + (size_t)k0 * N + (n0b < 0 ? 0 : n0b) + c32;
;     float va[8], vb[8];
; #pragma unroll
;     for (int i = 0; i < 8; ++i) { va[i] = sa[(size_t)(kq + 16 * i) * N]; vb[i] = sb[(size_t)(kq + 16 * i) * N]; }
;     __syncthreads();
; #pragma unroll
;     for (int i = 0; i < 8; ++i) { tl[(kq + 16 * i) * 33 + c32] = n0a < 0 ? 0.f : va[i]; tl[128 * 33 + (kq + 16 * i) * 33 + c32] = n0b < 0 ? 0.f : vb[i]; }
;     __syncthreads();
;     const int row = tid >> 4, kc = (tid & 15) * 8;
; #pragma unroll
;     for (int h = 0; h < 2; ++h) { const float* q = tl + h * 128 * 33 + kc * 33 + row;
;       u32x4 w; w.x = cvt_pk_bf16(q[0], q[33]); w.y = cvt_pk_bf16(q[66], q[99]); w.z = cvt_pk_bf16(q[132], q[165]); w.w = cvt_pk_bf16(q[198], q[231]);
;       *(u32x4*)(dst + (size_t)(p0 + h * 32 + row) * K + k0 + kc) = w; }
	ds_read_b32 v128, v43 offset:33792
	ds_read_b32 v129, v43 offset:33924
	ds_read_b32 v130, v43 offset:34056
	ds_read_b32 v131, v43 offset:34188
	ds_read_b32 v132, v43 offset:34320
	ds_read_b32 v133, v43 offset:34452
	ds_read_b32 v134, v43 offset:34584
	ds_read_b32 v135, v43 offset:34716
	ds_read_b32 v136, v44 offset:33792
	ds_read_b32 v137, v44 offset:33924
	ds_read_b32 v138, v44 offset:34056
	ds_read_b32 v139, v44 offset:34188
	ds_read_b32 v140, v44 offset:34320
	ds_read_b32 v141, v44 offset:34452
	ds_read_b32 v142, v44 offset:34584
	ds_read_b32 v143, v44 offset:34716
	s_waitcnt lgkmcnt(8)
	v_cvt_pk_bf16_f32 v48, v128, v129
	v_cvt_pk_bf16_f32 v49, v130, v131
	v_cvt_pk_bf16_f32 v50, v132, v133
	v_cvt_pk_bf16_f32 v51, v134, v135
	global_store_dwordx4 v45, v[48:51], s[84:85]
	s_waitcnt lgkmcnt(0)
	v_cvt_pk_bf16_f32 v52, v136, v137
	v_cvt_pk_bf16_f32 v53, v138, v139
	v_cvt_pk_bf16_f32 v54, v140, v141
	v_cvt_pk_bf16_f32 v55, v142, v143
	s_add_u32 s4, s84, 0x20000
	s_addc_u32 s5, s85, 0
	global_store_dwordx4 v45, v[52:55], s[4:5]
	s_add_u32 s84, s84, 0x400000
	s_addc_u32 s85, s85, 0
	s_waitcnt vmcnt(20)
	ds_write_b32 v42, v96 offset:0
	ds_write_b32 v42, v104 offset:16896
	ds_write_b32 v42, v97 offset:2112
	ds_write_b32 v42, v105 offset:19008
	ds_write_b32 v42, v98 offset:4224
	ds_write_b32 v42, v106 offset:21120
	ds_write_b32 v42, v99 offset:6336
	ds_write_b32 v42, v107 offset:23232
	ds_write_b32 v42, v100 offset:8448
	ds_write_b32 v42, v108 offset:25344
	ds_write_b32 v42, v101 offset:10560
	ds_write_b32 v42, v109 offset:27456
	ds_write_b32 v42, v102 offset:12672
	ds_write_b32 v42, v110 offset:29568
	ds_write_b32 v42, v103 offset:14784
	ds_write_b32 v42, v111 offset:31680
	s_waitcnt lgkmcnt(0)
	s_barrier
	ds_read_b32 v128, v43 offset:0
	ds_read_b32 v129, v43 offset:132
	ds_read_b32 v130, v43 offset:264
	ds_read_b32 v131, v43 offset:396
	ds_read_b32 v132, v43 offset:528
	ds_read_b32 v133, v43 offset:660
	ds_read_b32 v134, v43 offset:792
	ds_read_b32 v135, v43 offset:924
	ds_read_b32 v136, v44 offset:0
	ds_read_b32 v137, v44 offset:132
	ds_read_b32 v138, v44 offset:264
	ds_read_b32 v139, v44 offset:396
	ds_read_b32 v140, v44 offset:528
	ds_read_b32 v141, v44 offset:660
	ds_read_b32 v142, v44 offset:792
	ds_read_b32 v143, v44 offset:924
	s_waitcnt lgkmcnt(8)
	v_cvt_pk_bf16_f32 v48, v128, v129
	v_cvt_pk_bf16_f32 v49, v130, v131
	v_cvt_pk_bf16_f32 v50, v132, v133
	v_cvt_pk_bf16_f32 v51, v134, v135
	global_store_dwordx4 v45, v[48:51], s[84:85]
	s_waitcnt lgkmcnt(0)
	v_cvt_pk_bf16_f32 v52, v136, v137
	v_cvt_pk_bf16_f32 v53, v138, v139
	v_cvt_pk_bf16_f32 v54, v140, v141
	v_cvt_pk_bf16_f32 v55, v142, v143
	s_add_u32 s4, s84, 0x20000
	s_addc_u32 s5, s85, 0
	global_store_dwordx4 v45, v[52:55], s[4:5]
	s_add_u32 s84, s84, 0x400000
	s_addc_u32 s85, s85, 0
	s_waitcnt vmcnt(6)
	ds_write_b32 v42, v112 offset:33792
	ds_write_b32 v42, v120 offset:50688
	ds_write_b32 v42, v113 offset:35904
	ds_write_b32 v42, v121 offset:52800
	ds_write_b32 v42, v114 offset:38016
	ds_write_b32 v42, v122 offset:54912
	ds_write_b32 v42, v115 offset:40128
	ds_write_b32 v42, v123 offset:57024
	ds_write_b32 v42, v116 offset:42240
	ds_write_b32 v42, v124 offset:59136
	ds_write_b32 v42, v117 offset:44352
	ds_write_b32 v42, v125 offset:61248
	ds_write_b32 v42, v118 offset:46464
	ds_write_b32 v42, v126 offset:63360
	ds_write_b32 v42, v119 offset:48576
	ds_write_b32 v42, v127 offset:65472
	s_waitcnt lgkmcnt(0)
	s_barrier
	ds_read_b32 v128, v43 offset:33792
	ds_read_b32 v129, v43 offset:33924
	ds_read_b32 v130, v43 offset:34056
	ds_read_b32 v131, v43 offset:34188
	ds_read_b32 v132, v43 offset:34320
	ds_read_b32 v133, v43 offset:34452
	ds_read_b32 v134, v43 offset:34584
	ds_read_b32 v135, v43 offset:34716
	ds_read_b32 v136, v44 offset:33792
	ds_read_b32 v137, v44 offset:33924
	ds_read_b32 v138, v44 offset:34056
	ds_read_b32 v139, v44 offset:34188
	ds_read_b32 v140, v44 offset:34320
	ds_read_b32 v141, v44 offset:34452
	ds_read_b32 v142, v44 offset:34584
	ds_read_b32 v143, v44 offset:34716
	s_waitcnt lgkmcnt(8)
	v_cvt_pk_bf16_f32 v48, v128, v129
	v_cvt_pk_bf16_f32 v49, v130, v131
	v_cvt_pk_bf16_f32 v50, v132, v133
	v_cvt_pk_bf16_f32 v51, v134, v135
	global_store_dwordx4 v45, v[48:51], s[84:85]
	s_waitcnt lgkmcnt(0)
	v_cvt_pk_bf16_f32 v52, v136, v137
	v_cvt_pk_bf16_f32 v53, v138, v139
	v_cvt_pk_bf16_f32 v54, v140, v141
	v_cvt_pk_bf16_f32 v55, v142, v143
	s_add_u32 s4, s84, 0x20000
	s_addc_u32 s5, s85, 0
	global_store_dwordx4 v45, v[52:55], s[4:5]
	s_branch .LBB0_36
.Lwin_orig:
	s_movk_i32 s0, 0xf40
	v_mov_b32_e32 v5, 0x3d000
	v_mad_u32_u24 v6, v33, s0, v5
	v_mov_b32_e32 v5, 0x4c400
	v_mad_u32_u24 v8, v33, s0, v5
	v_mov_b32_e32 v5, 0x5b800
	v_mad_u32_u24 v10, v33, s0, v5
	v_mov_b32_e32 v5, 0x6ac00
	v_lshlrev_b32_e32 v2, 1, v32
	v_mov_b32_e32 v3, v1
	v_mul_u32_u24_e32 v4, 0xf40, v33
	v_mad_u32_u24 v12, v33, s0, v5
	v_lshl_add_u64 v[2:3], s[74:75], 0, v[2:3]
	s_mov_b32 s4, 0x3d000
	s_lshl_b32 s5, s14, 7
	s_lshl_b32 s6, s78, 7
	s_mov_b32 s1, 0
	v_lshlrev_b32_e32 v4, 2, v4
	v_mov_b32_e32 v5, v1
	s_mov_b32 s7, 0x7a000
	s_mov_b32 s15, 0xb7000
	v_lshlrev_b32_e32 v6, 2, v6
	v_mov_b32_e32 v7, v1
	v_lshlrev_b32_e32 v8, 2, v8
	v_mov_b32_e32 v9, v1
	v_lshlrev_b32_e32 v10, 2, v10
	v_mov_b32_e32 v11, v1
	v_lshlrev_b32_e32 v12, 2, v12
	v_mov_b32_e32 v13, v1
	v_add_u32_e32 v14, 0x4000, v22
	v_add_u32_e32 v15, 0x4400, v22
	s_mov_b32 s33, s14
	s_branch .LBB0_21
